# sample attention second half hand-rewritten: V fragments prefetched, exp/pack/PV MFMAs pipelined per 16-key group; residual epilogue loads batched
# speedup vs baseline: 1.0098x; 1.0098x over previous
.LBB0_287:
	v_lshl_add_u64 v[64:65], v[88:89], 0, s[42:43]
	global_load_dwordx4 v[80:83], v[64:65], off
	v_lshl_add_u64 v[64:65], v[90:91], 0, s[42:43]
	global_load_dwordx4 v[72:75], v[64:65], off
	v_lshl_add_u64 v[64:65], v[92:93], 0, s[42:43]
	global_load_dwordx4 v[76:79], v[64:65], off
	v_lshl_add_u64 v[64:65], v[94:95], 0, s[42:43]
	v_lshl_add_u64 v[68:69], v[96:97], 0, s[42:43]
	v_lshl_add_u64 v[84:85], v[98:99], 0, s[42:43]
	global_load_dwordx4 v[64:67], v[64:65], off
	s_bitcmp1_b32 s3, 0
	global_load_dwordx4 v[68:71], v[68:69], off
	s_cselect_b32 s22, 0, 0xd800
	global_load_dwordx4 v[84:87], v[84:85], off
	s_cselect_b32 s23, 0xd800, 0
	s_add_i32 s34, s22, 0
	v_add3_u32 v134, s34, v108, v103
	ds_read_b128 v[110:113], v134 offset:4608
	v_add3_u32 v135, s34, v104, v103
	ds_read_b128 v[114:117], v135 offset:41472
	s_waitcnt lgkmcnt(0)
	v_mfma_f32_32x32x16_bf16 v[0:15], v[110:113], v[114:117], v[0:15]
	ds_read_b128 v[118:121], v134
	ds_read_b128 v[122:125], v134 offset:32
	s_add_i32 s22, s23, 0
	s_add_u32 s42, s42, 0x80
	s_addc_u32 s43, s43, 0
	s_add_i32 s3, s3, 1
	s_cmpk_eq_i32 s42, 0x780
	s_waitcnt lgkmcnt(1)
	v_mfma_f32_32x32x16_bf16 v[16:31], v[118:121], v[114:117], v[16:31]
	ds_read_b128 v[130:133], v135 offset:36864
	ds_read_b128 v[126:129], v134 offset:4640
	s_waitcnt lgkmcnt(1)
	v_mfma_f32_32x32x16_bf16 v[48:63], v[118:121], v[130:133], v[48:63]
	ds_read_b128 v[142:145], v135 offset:36896
	ds_read_b128 v[146:149], v135 offset:41504
	v_mfma_f32_32x32x16_bf16 v[32:47], v[110:113], v[130:133], v[32:47]
	ds_read_b128 v[110:113], v134 offset:4672
	ds_read_b128 v[114:117], v135 offset:41536
	s_waitcnt lgkmcnt(3)
	v_mfma_f32_32x32x16_bf16 v[48:63], v[122:125], v[142:145], v[48:63]
	ds_read_b128 v[118:121], v134 offset:64
	ds_read_b128 v[130:133], v135 offset:36928
	s_waitcnt lgkmcnt(4)
	v_mfma_f32_32x32x16_bf16 v[16:31], v[122:125], v[146:149], v[16:31]
	ds_read_b128 v[122:125], v134 offset:96
	v_mfma_f32_32x32x16_bf16 v[32:47], v[126:129], v[142:145], v[32:47]
	ds_read_b128 v[142:145], v135 offset:36960
	v_mfma_f32_32x32x16_bf16 v[0:15], v[126:129], v[146:149], v[0:15]
	ds_read_b128 v[126:129], v134 offset:4704
	ds_read_b128 v[146:149], v135 offset:41568
	s_waitcnt lgkmcnt(4)
	v_mfma_f32_32x32x16_bf16 v[48:63], v[118:121], v[130:133], v[48:63]
	v_mfma_f32_32x32x16_bf16 v[16:31], v[118:121], v[114:117], v[16:31]
	v_mfma_f32_32x32x16_bf16 v[32:47], v[110:113], v[130:133], v[32:47]
	v_mfma_f32_32x32x16_bf16 v[0:15], v[110:113], v[114:117], v[0:15]
	v_add_u32_e32 v110, s22, v136
	v_add_u32_e32 v111, v110, v105
	s_waitcnt vmcnt(5)
	ds_write_b128 v111, v[80:83]
	v_add_u32_e32 v80, v110, v106
	s_waitcnt vmcnt(4)
	ds_write_b128 v80, v[72:75]
	v_add_u32_e32 v72, v110, v107
	s_waitcnt lgkmcnt(4)
	v_mfma_f32_32x32x16_bf16 v[48:63], v[122:125], v[142:145], v[48:63]
	s_waitcnt vmcnt(3)
	ds_write_b128 v72, v[76:79]
	v_add_u32_e32 v72, v110, v109
	s_waitcnt vmcnt(2)
	ds_write_b128 v72, v[64:67]
	s_waitcnt lgkmcnt(4)
	v_mfma_f32_32x32x16_bf16 v[16:31], v[122:125], v[146:149], v[16:31]
	s_waitcnt vmcnt(1)
	ds_write_b128 v111, v[68:71] offset:36864
	s_waitcnt vmcnt(0)
	ds_write_b128 v80, v[84:87] offset:36864
	s_waitcnt lgkmcnt(0)
	s_barrier
	v_mfma_f32_32x32x16_bf16 v[32:47], v[126:129], v[142:145], v[32:47]
	v_mfma_f32_32x32x16_bf16 v[0:15], v[126:129], v[146:149], v[0:15]
	s_cbranch_scc0 .LBB0_287
	v_add3_u32 v96, s22, v108, v103
	ds_read_b128 v[64:67], v96 offset:4608
	v_add3_u32 v97, s22, v104, v103
	ds_read_b128 v[68:71], v97 offset:41472
	v_readlane_b32 s76, v251, 2
	v_readlane_b32 s82, v251, 8
	v_readlane_b32 s83, v251, 9
	s_movk_i32 s3, 0x4000
	s_mov_b32 s6, 0x9000
	s_waitcnt lgkmcnt(0)
	v_mfma_f32_32x32x16_bf16 v[0:15], v[64:67], v[68:71], v[0:15]
	ds_read_b128 v[72:75], v96
	ds_read_b128 v[76:79], v96 offset:32
	s_mov_b32 s7, 0xd000
	v_readlane_b32 s77, v251, 3
	v_readlane_b32 s78, v251, 4
	v_readlane_b32 s79, v251, 5
	v_readlane_b32 s80, v251, 6
	s_waitcnt lgkmcnt(1)
	v_mfma_f32_32x32x16_bf16 v[16:31], v[72:75], v[68:71], v[16:31]
	ds_read_b128 v[84:87], v97 offset:36864
	ds_read_b128 v[80:83], v96 offset:4640
	v_readlane_b32 s81, v251, 7
	s_waitcnt lgkmcnt(1)
	v_mfma_f32_32x32x16_bf16 v[48:63], v[72:75], v[84:87], v[48:63]
	ds_read_b128 v[88:91], v97 offset:36896
	ds_read_b128 v[92:95], v97 offset:41504
	v_mfma_f32_32x32x16_bf16 v[32:47], v[64:67], v[84:87], v[32:47]
	ds_read_b128 v[64:67], v96 offset:4672
	ds_read_b128 v[68:71], v97 offset:41536
	s_waitcnt lgkmcnt(3)
	v_mfma_f32_32x32x16_bf16 v[48:63], v[76:79], v[88:91], v[48:63]
	ds_read_b128 v[72:75], v96 offset:64
	ds_read_b128 v[84:87], v97 offset:36928
	s_waitcnt lgkmcnt(4)
	v_mfma_f32_32x32x16_bf16 v[16:31], v[76:79], v[92:95], v[16:31]
	ds_read_b128 v[76:79], v96 offset:96
	v_mfma_f32_32x32x16_bf16 v[32:47], v[80:83], v[88:91], v[32:47]
	ds_read_b128 v[88:91], v97 offset:36960
	v_mfma_f32_32x32x16_bf16 v[0:15], v[80:83], v[92:95], v[0:15]
	ds_read_b128 v[80:83], v96 offset:4704
	ds_read_b128 v[92:95], v97 offset:41568
	s_waitcnt lgkmcnt(0)
	s_barrier
	v_mfma_f32_32x32x16_bf16 v[48:63], v[72:75], v[84:87], v[48:63]
	v_mfma_f32_32x32x16_bf16 v[16:31], v[72:75], v[68:71], v[16:31]
	v_mfma_f32_32x32x16_bf16 v[32:47], v[64:67], v[84:87], v[32:47]
	v_mfma_f32_32x32x16_bf16 v[0:15], v[64:67], v[68:71], v[0:15]
	v_add_u32_e32 v65, s40, v102
	v_add_u32_e32 v64, 0xffffe000, v65
	v_lshrrev_b32_e32 v64, 12, v64
	v_lshrrev_b32_e32 v66, 3, v100
	v_mad_u32_u24 v64, v64, s4, s4
	v_cmp_lt_i32_e32 vcc, s5, v65
	v_and_or_b32 v66, v66, 4, v65
	v_ashrrev_i32_e32 v67, 31, v66
	v_cndmask_b32_e32 v136, 0, v64, vcc
	v_or_b32_e32 v64, s2, v101
	v_mfma_f32_32x32x16_bf16 v[48:63], v[76:79], v[88:91], v[48:63]
	v_ashrrev_i32_e32 v65, 31, v64
	v_lshl_add_u64 v[68:69], v[136:137], 2, s[0:1]
	v_lshlrev_b64 v[84:85], 1, v[64:65]
	s_movk_i32 s2, 0x1000
	s_movk_i32 s5, 0x5000
	s_mov_b32 s4, 0x8000
	v_mfma_f32_32x32x16_bf16 v[16:31], v[76:79], v[92:95], v[16:31]
	v_mfma_f32_32x32x16_bf16 v[32:47], v[80:83], v[88:91], v[32:47]
	v_mfma_f32_32x32x16_bf16 v[0:15], v[80:83], v[92:95], v[0:15]
	v_or_b32_e32 v82, 32, v66
	v_lshlrev_b64 v[66:67], 11, v[66:67]
	v_lshl_add_u64 v[66:67], s[82:83], 0, v[66:67]
	v_lshl_add_u64 v[80:81], v[64:65], 2, v[68:69]
	v_lshl_add_u64 v[64:65], v[66:67], 0, v[84:85]
	v_ashrrev_i32_e32 v83, 31, v82
	v_lshlrev_b64 v[86:87], 11, v[82:83]
	v_lshl_add_u64 v[86:87], s[82:83], 0, v[86:87]
	v_lshl_add_u64 v[86:87], v[86:87], 0, v[84:85]
	global_load_dword v104, v[80:81], off
	global_load_dword v105, v[80:81], off offset:128
	v_add_co_u32_e32 v88, vcc, 0x1000, v64
	v_addc_co_u32_e32 v89, vcc, 0, v65, vcc
	v_add_co_u32_e32 v90, vcc, 0x5000, v64
	v_addc_co_u32_e32 v91, vcc, 0, v65, vcc
	v_add_co_u32_e32 v92, vcc, 0x9000, v64
	v_addc_co_u32_e32 v93, vcc, 0, v65, vcc
	v_add_co_u32_e32 v94, vcc, 0xd000, v64
	v_addc_co_u32_e32 v95, vcc, 0, v65, vcc
	v_add_co_u32_e32 v96, vcc, 0x1000, v86
	v_addc_co_u32_e32 v97, vcc, 0, v87, vcc
	v_add_co_u32_e32 v98, vcc, 0x5000, v86
	v_addc_co_u32_e32 v99, vcc, 0, v87, vcc
	v_add_co_u32_e32 v100, vcc, 0x9000, v86
	v_addc_co_u32_e32 v101, vcc, 0, v87, vcc
	v_add_co_u32_e32 v102, vcc, 0xd000, v86
	v_addc_co_u32_e32 v103, vcc, 0, v87, vcc
	global_load_ushort v106, v[88:89], off offset:-4096
	global_load_ushort v107, v[88:89], off offset:-2048
	global_load_ushort v108, v[88:89], off
	global_load_ushort v109, v[88:89], off offset:2048
	global_load_ushort v110, v[90:91], off offset:-4096
	global_load_ushort v111, v[90:91], off offset:-2048
	global_load_ushort v112, v[90:91], off
	global_load_ushort v113, v[90:91], off offset:2048
	global_load_ushort v114, v[92:93], off offset:-4096
	global_load_ushort v115, v[92:93], off offset:-2048
	global_load_ushort v116, v[92:93], off
	global_load_ushort v117, v[92:93], off offset:2048
	global_load_ushort v118, v[94:95], off offset:-4096
	global_load_ushort v119, v[94:95], off offset:-2048
	global_load_ushort v120, v[94:95], off
	global_load_ushort v121, v[94:95], off offset:2048
	global_load_ushort v142, v[96:97], off offset:-4096
	global_load_ushort v143, v[96:97], off offset:-2048
	global_load_ushort v144, v[96:97], off
	global_load_ushort v145, v[96:97], off offset:2048
	global_load_ushort v146, v[98:99], off offset:-4096
	global_load_ushort v147, v[98:99], off offset:-2048
	global_load_ushort v148, v[98:99], off
	global_load_ushort v149, v[98:99], off offset:2048
	global_load_ushort v150, v[100:101], off offset:-4096
	global_load_ushort v151, v[100:101], off offset:-2048
	global_load_ushort v152, v[100:101], off
	global_load_ushort v153, v[100:101], off offset:2048
	global_load_ushort v154, v[102:103], off offset:-4096
	global_load_ushort v155, v[102:103], off offset:-2048
	global_load_ushort v156, v[102:103], off
	global_load_ushort v157, v[102:103], off offset:2048
	s_waitcnt vmcnt(16)
	global_load_ushort v158, v[88:89], off offset:-4032
	global_load_ushort v159, v[88:89], off offset:-1984
	global_load_ushort v160, v[88:89], off offset:64
	global_load_ushort v161, v[88:89], off offset:2112
	global_load_ushort v162, v[90:91], off offset:-4032
	global_load_ushort v163, v[90:91], off offset:-1984
	global_load_ushort v164, v[90:91], off offset:64
	global_load_ushort v165, v[90:91], off offset:2112
	global_load_ushort v166, v[92:93], off offset:-4032
	global_load_ushort v167, v[92:93], off offset:-1984
	global_load_ushort v168, v[92:93], off offset:64
	global_load_ushort v169, v[92:93], off offset:2112
	global_load_ushort v170, v[94:95], off offset:-4032
	global_load_ushort v171, v[94:95], off offset:-1984
	global_load_ushort v172, v[94:95], off offset:64
	global_load_ushort v173, v[94:95], off offset:2112
	v_lshlrev_b32_e32 v106, 16, v106
	v_fmac_f32_e32 v106, v48, v104
	v_cvt_pk_bf16_f32 v106, v106, v106
	global_store_short v[88:89], v106, off offset:-4096
	v_lshlrev_b32_e32 v107, 16, v107
	v_fmac_f32_e32 v107, v49, v104
	v_cvt_pk_bf16_f32 v107, v107, v107
	global_store_short v[88:89], v107, off offset:-2048
	v_lshlrev_b32_e32 v108, 16, v108
	v_fmac_f32_e32 v108, v50, v104
	v_cvt_pk_bf16_f32 v108, v108, v108
	global_store_short v[88:89], v108, off
	v_lshlrev_b32_e32 v109, 16, v109
	v_fmac_f32_e32 v109, v51, v104
	v_cvt_pk_bf16_f32 v109, v109, v109
	global_store_short v[88:89], v109, off offset:2048
	v_lshlrev_b32_e32 v110, 16, v110
	v_fmac_f32_e32 v110, v52, v104
	v_cvt_pk_bf16_f32 v110, v110, v110
	global_store_short v[90:91], v110, off offset:-4096
	v_lshlrev_b32_e32 v111, 16, v111
	v_fmac_f32_e32 v111, v53, v104
	v_cvt_pk_bf16_f32 v111, v111, v111
	global_store_short v[90:91], v111, off offset:-2048
	v_lshlrev_b32_e32 v112, 16, v112
	v_fmac_f32_e32 v112, v54, v104
	v_cvt_pk_bf16_f32 v112, v112, v112
	global_store_short v[90:91], v112, off
	v_lshlrev_b32_e32 v113, 16, v113
	v_fmac_f32_e32 v113, v55, v104
	v_cvt_pk_bf16_f32 v113, v113, v113
	global_store_short v[90:91], v113, off offset:2048
	v_lshlrev_b32_e32 v114, 16, v114
	v_fmac_f32_e32 v114, v56, v104
	v_cvt_pk_bf16_f32 v114, v114, v114
	global_store_short v[92:93], v114, off offset:-4096
	v_lshlrev_b32_e32 v115, 16, v115
	v_fmac_f32_e32 v115, v57, v104
	v_cvt_pk_bf16_f32 v115, v115, v115
	global_store_short v[92:93], v115, off offset:-2048
	v_lshlrev_b32_e32 v116, 16, v116
	v_fmac_f32_e32 v116, v58, v104
	v_cvt_pk_bf16_f32 v116, v116, v116
	global_store_short v[92:93], v116, off
	v_lshlrev_b32_e32 v117, 16, v117
	v_fmac_f32_e32 v117, v59, v104
	v_cvt_pk_bf16_f32 v117, v117, v117
	global_store_short v[92:93], v117, off offset:2048
	v_lshlrev_b32_e32 v118, 16, v118
	v_fmac_f32_e32 v118, v60, v104
	v_cvt_pk_bf16_f32 v118, v118, v118
	global_store_short v[94:95], v118, off offset:-4096
	v_lshlrev_b32_e32 v119, 16, v119
	v_fmac_f32_e32 v119, v61, v104
	v_cvt_pk_bf16_f32 v119, v119, v119
	global_store_short v[94:95], v119, off offset:-2048
	v_lshlrev_b32_e32 v120, 16, v120
	v_fmac_f32_e32 v120, v62, v104
	v_cvt_pk_bf16_f32 v120, v120, v120
	global_store_short v[94:95], v120, off
	v_lshlrev_b32_e32 v121, 16, v121
	v_fmac_f32_e32 v121, v63, v104
	v_cvt_pk_bf16_f32 v121, v121, v121
	global_store_short v[94:95], v121, off offset:2048
	s_waitcnt vmcnt(32)
	global_load_ushort v188, v[96:97], off offset:-4032
	global_load_ushort v189, v[96:97], off offset:-1984
	global_load_ushort v190, v[96:97], off offset:64
	global_load_ushort v191, v[96:97], off offset:2112
	global_load_ushort v192, v[98:99], off offset:-4032
	global_load_ushort v193, v[98:99], off offset:-1984
	global_load_ushort v194, v[98:99], off offset:64
	global_load_ushort v195, v[98:99], off offset:2112
	global_load_ushort v196, v[100:101], off offset:-4032
	global_load_ushort v197, v[100:101], off offset:-1984
	global_load_ushort v198, v[100:101], off offset:64
	global_load_ushort v199, v[100:101], off offset:2112
	global_load_ushort v200, v[102:103], off offset:-4032
	global_load_ushort v201, v[102:103], off offset:-1984
	global_load_ushort v202, v[102:103], off offset:64
	global_load_ushort v203, v[102:103], off offset:2112
	v_lshlrev_b32_e32 v142, 16, v142
	v_fmac_f32_e32 v142, v32, v104
	v_cvt_pk_bf16_f32 v142, v142, v142
	global_store_short v[96:97], v142, off offset:-4096
	v_lshlrev_b32_e32 v143, 16, v143
	v_fmac_f32_e32 v143, v33, v104
	v_cvt_pk_bf16_f32 v143, v143, v143
	global_store_short v[96:97], v143, off offset:-2048
	v_lshlrev_b32_e32 v144, 16, v144
	v_fmac_f32_e32 v144, v34, v104
	v_cvt_pk_bf16_f32 v144, v144, v144
	global_store_short v[96:97], v144, off
	v_lshlrev_b32_e32 v145, 16, v145
	v_fmac_f32_e32 v145, v35, v104
	v_cvt_pk_bf16_f32 v145, v145, v145
	global_store_short v[96:97], v145, off offset:2048
	v_lshlrev_b32_e32 v146, 16, v146
	v_fmac_f32_e32 v146, v36, v104
	v_cvt_pk_bf16_f32 v146, v146, v146
	global_store_short v[98:99], v146, off offset:-4096
	v_lshlrev_b32_e32 v147, 16, v147
	v_fmac_f32_e32 v147, v37, v104
	v_cvt_pk_bf16_f32 v147, v147, v147
	global_store_short v[98:99], v147, off offset:-2048
	v_lshlrev_b32_e32 v148, 16, v148
	v_fmac_f32_e32 v148, v38, v104
	v_cvt_pk_bf16_f32 v148, v148, v148
	global_store_short v[98:99], v148, off
	v_lshlrev_b32_e32 v149, 16, v149
	v_fmac_f32_e32 v149, v39, v104
	v_cvt_pk_bf16_f32 v149, v149, v149
	global_store_short v[98:99], v149, off offset:2048
	v_lshlrev_b32_e32 v150, 16, v150
	v_fmac_f32_e32 v150, v40, v104
	v_cvt_pk_bf16_f32 v150, v150, v150
	global_store_short v[100:101], v150, off offset:-4096
	v_lshlrev_b32_e32 v151, 16, v151
	v_fmac_f32_e32 v151, v41, v104
	v_cvt_pk_bf16_f32 v151, v151, v151
	global_store_short v[100:101], v151, off offset:-2048
	v_lshlrev_b32_e32 v152, 16, v152
	v_fmac_f32_e32 v152, v42, v104
	v_cvt_pk_bf16_f32 v152, v152, v152
	global_store_short v[100:101], v152, off
	v_lshlrev_b32_e32 v153, 16, v153
	v_fmac_f32_e32 v153, v43, v104
	v_cvt_pk_bf16_f32 v153, v153, v153
	global_store_short v[100:101], v153, off offset:2048
	v_lshlrev_b32_e32 v154, 16, v154
	v_fmac_f32_e32 v154, v44, v104
	v_cvt_pk_bf16_f32 v154, v154, v154
	global_store_short v[102:103], v154, off offset:-4096
	v_lshlrev_b32_e32 v155, 16, v155
	v_fmac_f32_e32 v155, v45, v104
	v_cvt_pk_bf16_f32 v155, v155, v155
	global_store_short v[102:103], v155, off offset:-2048
	v_lshlrev_b32_e32 v156, 16, v156
	v_fmac_f32_e32 v156, v46, v104
	v_cvt_pk_bf16_f32 v156, v156, v156
	global_store_short v[102:103], v156, off
	v_lshlrev_b32_e32 v157, 16, v157
	v_fmac_f32_e32 v157, v47, v104
	v_cvt_pk_bf16_f32 v157, v157, v157
	global_store_short v[102:103], v157, off offset:2048
	s_waitcnt vmcnt(48)
	v_lshlrev_b32_e32 v158, 16, v158
	v_fmac_f32_e32 v158, v16, v105
	v_cvt_pk_bf16_f32 v158, v158, v158
	global_store_short v[88:89], v158, off offset:-4032
	v_lshlrev_b32_e32 v159, 16, v159
	v_fmac_f32_e32 v159, v17, v105
	v_cvt_pk_bf16_f32 v159, v159, v159
	global_store_short v[88:89], v159, off offset:-1984
	v_lshlrev_b32_e32 v160, 16, v160
	v_fmac_f32_e32 v160, v18, v105
	v_cvt_pk_bf16_f32 v160, v160, v160
	global_store_short v[88:89], v160, off offset:64
	v_lshlrev_b32_e32 v161, 16, v161
	v_fmac_f32_e32 v161, v19, v105
	v_cvt_pk_bf16_f32 v161, v161, v161
	global_store_short v[88:89], v161, off offset:2112
	v_lshlrev_b32_e32 v162, 16, v162
	v_fmac_f32_e32 v162, v20, v105
	v_cvt_pk_bf16_f32 v162, v162, v162
	global_store_short v[90:91], v162, off offset:-4032
	v_lshlrev_b32_e32 v163, 16, v163
	v_fmac_f32_e32 v163, v21, v105
	v_cvt_pk_bf16_f32 v163, v163, v163
	global_store_short v[90:91], v163, off offset:-1984
	v_lshlrev_b32_e32 v164, 16, v164
	v_fmac_f32_e32 v164, v22, v105
	v_cvt_pk_bf16_f32 v164, v164, v164
	global_store_short v[90:91], v164, off offset:64
	v_lshlrev_b32_e32 v165, 16, v165
	v_fmac_f32_e32 v165, v23, v105
	v_cvt_pk_bf16_f32 v165, v165, v165
	global_store_short v[90:91], v165, off offset:2112
	v_lshlrev_b32_e32 v166, 16, v166
	v_fmac_f32_e32 v166, v24, v105
	v_cvt_pk_bf16_f32 v166, v166, v166
	global_store_short v[92:93], v166, off offset:-4032
	v_lshlrev_b32_e32 v167, 16, v167
	v_fmac_f32_e32 v167, v25, v105
	v_cvt_pk_bf16_f32 v167, v167, v167
	global_store_short v[92:93], v167, off offset:-1984
	v_lshlrev_b32_e32 v168, 16, v168
	v_fmac_f32_e32 v168, v26, v105
	v_cvt_pk_bf16_f32 v168, v168, v168
	global_store_short v[92:93], v168, off offset:64
	v_lshlrev_b32_e32 v169, 16, v169
	v_fmac_f32_e32 v169, v27, v105
	v_cvt_pk_bf16_f32 v169, v169, v169
	global_store_short v[92:93], v169, off offset:2112
	v_lshlrev_b32_e32 v170, 16, v170
	v_fmac_f32_e32 v170, v28, v105
	v_cvt_pk_bf16_f32 v170, v170, v170
	global_store_short v[94:95], v170, off offset:-4032
	v_lshlrev_b32_e32 v171, 16, v171
	v_fmac_f32_e32 v171, v29, v105
	v_cvt_pk_bf16_f32 v171, v171, v171
	global_store_short v[94:95], v171, off offset:-1984
	v_lshlrev_b32_e32 v172, 16, v172
	v_fmac_f32_e32 v172, v30, v105
	v_cvt_pk_bf16_f32 v172, v172, v172
	global_store_short v[94:95], v172, off offset:64
	v_lshlrev_b32_e32 v173, 16, v173
	v_fmac_f32_e32 v173, v31, v105
	v_cvt_pk_bf16_f32 v173, v173, v173
	global_store_short v[94:95], v173, off offset:2112
	s_waitcnt vmcnt(32)
	v_lshlrev_b32_e32 v188, 16, v188
	v_fmac_f32_e32 v188, v0, v105
	v_cvt_pk_bf16_f32 v188, v188, v188
	global_store_short v[96:97], v188, off offset:-4032
	v_lshlrev_b32_e32 v189, 16, v189
	v_fmac_f32_e32 v189, v1, v105
	v_cvt_pk_bf16_f32 v189, v189, v189
	global_store_short v[96:97], v189, off offset:-1984
	v_lshlrev_b32_e32 v190, 16, v190
	v_fmac_f32_e32 v190, v2, v105
	v_cvt_pk_bf16_f32 v190, v190, v190
	global_store_short v[96:97], v190, off offset:64
	v_lshlrev_b32_e32 v191, 16, v191
	v_fmac_f32_e32 v191, v3, v105
	v_cvt_pk_bf16_f32 v191, v191, v191
	global_store_short v[96:97], v191, off offset:2112
	v_lshlrev_b32_e32 v192, 16, v192
	v_fmac_f32_e32 v192, v4, v105
	v_cvt_pk_bf16_f32 v192, v192, v192
	global_store_short v[98:99], v192, off offset:-4032
	v_lshlrev_b32_e32 v193, 16, v193
	v_fmac_f32_e32 v193, v5, v105
	v_cvt_pk_bf16_f32 v193, v193, v193
	global_store_short v[98:99], v193, off offset:-1984
	v_lshlrev_b32_e32 v194, 16, v194
	v_fmac_f32_e32 v194, v6, v105
	v_cvt_pk_bf16_f32 v194, v194, v194
	global_store_short v[98:99], v194, off offset:64
	v_lshlrev_b32_e32 v195, 16, v195
	v_fmac_f32_e32 v195, v7, v105
	v_cvt_pk_bf16_f32 v195, v195, v195
	global_store_short v[98:99], v195, off offset:2112
	v_lshlrev_b32_e32 v196, 16, v196
	v_fmac_f32_e32 v196, v8, v105
	v_cvt_pk_bf16_f32 v196, v196, v196
	global_store_short v[100:101], v196, off offset:-4032
	v_lshlrev_b32_e32 v197, 16, v197
	v_fmac_f32_e32 v197, v9, v105
	v_cvt_pk_bf16_f32 v197, v197, v197
	global_store_short v[100:101], v197, off offset:-1984
	v_lshlrev_b32_e32 v198, 16, v198
	v_fmac_f32_e32 v198, v10, v105
	v_cvt_pk_bf16_f32 v198, v198, v198
	global_store_short v[100:101], v198, off offset:64
	v_lshlrev_b32_e32 v199, 16, v199
	v_fmac_f32_e32 v199, v11, v105
	v_cvt_pk_bf16_f32 v199, v199, v199
	global_store_short v[100:101], v199, off offset:2112
	v_lshlrev_b32_e32 v200, 16, v200
	v_fmac_f32_e32 v200, v12, v105
	v_cvt_pk_bf16_f32 v200, v200, v200
	global_store_short v[102:103], v200, off offset:-4032
	v_lshlrev_b32_e32 v201, 16, v201
	v_fmac_f32_e32 v201, v13, v105
	v_cvt_pk_bf16_f32 v201, v201, v201
	global_store_short v[102:103], v201, off offset:-1984
	v_lshlrev_b32_e32 v202, 16, v202
	v_fmac_f32_e32 v202, v14, v105
	v_cvt_pk_bf16_f32 v202, v202, v202
	global_store_short v[102:103], v202, off offset:64
	v_lshlrev_b32_e32 v203, 16, v203
	v_fmac_f32_e32 v203, v15, v105
	v_cvt_pk_bf16_f32 v203, v203, v203
	global_store_short v[102:103], v203, off offset:2112
	v_readlane_b32 s2, v252, 33
	s_add_i32 s44, s44, s2
	s_cmp_gt_i32 s44, 31
	s_cbranch_scc0 .LBB0_286

.LBB0_345:
	v_lshl_add_u64 v[64:65], v[88:89], 0, s[42:43]
	global_load_dwordx4 v[80:83], v[64:65], off
	v_lshl_add_u64 v[64:65], v[90:91], 0, s[42:43]
	global_load_dwordx4 v[72:75], v[64:65], off
	v_lshl_add_u64 v[64:65], v[92:93], 0, s[42:43]
	global_load_dwordx4 v[76:79], v[64:65], off
	v_lshl_add_u64 v[64:65], v[94:95], 0, s[42:43]
	v_lshl_add_u64 v[68:69], v[96:97], 0, s[42:43]
	v_lshl_add_u64 v[84:85], v[98:99], 0, s[42:43]
	global_load_dwordx4 v[64:67], v[64:65], off
	s_bitcmp1_b32 s3, 0
	global_load_dwordx4 v[68:71], v[68:69], off
	s_cselect_b32 s22, 0, 0xd800
	global_load_dwordx4 v[84:87], v[84:85], off
	s_cselect_b32 s23, 0xd800, 0
	s_add_i32 s34, s22, 0
	v_add3_u32 v134, s34, v108, v103
	ds_read_b128 v[110:113], v134 offset:4608
	v_add3_u32 v135, s34, v104, v103
	ds_read_b128 v[114:117], v135 offset:41472
	s_waitcnt lgkmcnt(0)
	v_mfma_f32_32x32x16_bf16 v[0:15], v[110:113], v[114:117], v[0:15]
	ds_read_b128 v[118:121], v134
	ds_read_b128 v[122:125], v134 offset:32
	s_add_i32 s22, s23, 0
	s_add_u32 s42, s42, 0x80
	s_addc_u32 s43, s43, 0
	s_add_i32 s3, s3, 1
	s_cmpk_eq_i32 s42, 0x780
	s_waitcnt lgkmcnt(1)
	v_mfma_f32_32x32x16_bf16 v[16:31], v[118:121], v[114:117], v[16:31]
	ds_read_b128 v[130:133], v135 offset:36864
	ds_read_b128 v[126:129], v134 offset:4640
	s_waitcnt lgkmcnt(1)
	v_mfma_f32_32x32x16_bf16 v[48:63], v[118:121], v[130:133], v[48:63]
	ds_read_b128 v[142:145], v135 offset:36896
	ds_read_b128 v[146:149], v135 offset:41504
	v_mfma_f32_32x32x16_bf16 v[32:47], v[110:113], v[130:133], v[32:47]
	ds_read_b128 v[110:113], v134 offset:4672
	ds_read_b128 v[114:117], v135 offset:41536
	s_waitcnt lgkmcnt(3)
	v_mfma_f32_32x32x16_bf16 v[48:63], v[122:125], v[142:145], v[48:63]
	ds_read_b128 v[118:121], v134 offset:64
	ds_read_b128 v[130:133], v135 offset:36928
	s_waitcnt lgkmcnt(4)
	v_mfma_f32_32x32x16_bf16 v[16:31], v[122:125], v[146:149], v[16:31]
	ds_read_b128 v[122:125], v134 offset:96
	v_mfma_f32_32x32x16_bf16 v[32:47], v[126:129], v[142:145], v[32:47]
	ds_read_b128 v[142:145], v135 offset:36960
	v_mfma_f32_32x32x16_bf16 v[0:15], v[126:129], v[146:149], v[0:15]
	ds_read_b128 v[126:129], v134 offset:4704
	ds_read_b128 v[146:149], v135 offset:41568
	s_waitcnt lgkmcnt(4)
	v_mfma_f32_32x32x16_bf16 v[48:63], v[118:121], v[130:133], v[48:63]
	v_mfma_f32_32x32x16_bf16 v[16:31], v[118:121], v[114:117], v[16:31]
	v_mfma_f32_32x32x16_bf16 v[32:47], v[110:113], v[130:133], v[32:47]
	v_mfma_f32_32x32x16_bf16 v[0:15], v[110:113], v[114:117], v[0:15]
	v_add_u32_e32 v110, s22, v136
	v_add_u32_e32 v111, v110, v105
	s_waitcnt vmcnt(5)
	ds_write_b128 v111, v[80:83]
	v_add_u32_e32 v80, v110, v106
	s_waitcnt vmcnt(4)
	ds_write_b128 v80, v[72:75]
	v_add_u32_e32 v72, v110, v107
	s_waitcnt lgkmcnt(4)
	v_mfma_f32_32x32x16_bf16 v[48:63], v[122:125], v[142:145], v[48:63]
	s_waitcnt vmcnt(3)
	ds_write_b128 v72, v[76:79]
	v_add_u32_e32 v72, v110, v109
	s_waitcnt vmcnt(2)
	ds_write_b128 v72, v[64:67]
	s_waitcnt lgkmcnt(4)
	v_mfma_f32_32x32x16_bf16 v[16:31], v[122:125], v[146:149], v[16:31]
	s_waitcnt vmcnt(1)
	ds_write_b128 v111, v[68:71] offset:36864
	s_waitcnt vmcnt(0)
	ds_write_b128 v80, v[84:87] offset:36864
	s_waitcnt lgkmcnt(0)
	s_barrier
	v_mfma_f32_32x32x16_bf16 v[32:47], v[126:129], v[142:145], v[32:47]
	v_mfma_f32_32x32x16_bf16 v[0:15], v[126:129], v[146:149], v[0:15]
	s_cbranch_scc0 .LBB0_345
	v_add3_u32 v96, s22, v108, v103
	ds_read_b128 v[64:67], v96 offset:4608
	v_add3_u32 v97, s22, v104, v103
	ds_read_b128 v[68:71], v97 offset:41472
	v_readlane_b32 s72, v251, 2
	v_readlane_b32 s78, v251, 8
	v_readlane_b32 s79, v251, 9
	s_movk_i32 s3, 0x4000
	s_mov_b32 s6, 0x9000
	s_waitcnt lgkmcnt(0)
	v_mfma_f32_32x32x16_bf16 v[0:15], v[64:67], v[68:71], v[0:15]
	ds_read_b128 v[72:75], v96
	ds_read_b128 v[76:79], v96 offset:32
	s_mov_b32 s7, 0xd000
	v_readlane_b32 s73, v251, 3
	v_readlane_b32 s74, v251, 4
	v_readlane_b32 s75, v251, 5
	v_readlane_b32 s76, v251, 6
	s_waitcnt lgkmcnt(1)
	v_mfma_f32_32x32x16_bf16 v[16:31], v[72:75], v[68:71], v[16:31]
	ds_read_b128 v[84:87], v97 offset:36864
	ds_read_b128 v[80:83], v96 offset:4640
	v_readlane_b32 s77, v251, 7
	s_waitcnt lgkmcnt(1)
	v_mfma_f32_32x32x16_bf16 v[48:63], v[72:75], v[84:87], v[48:63]
	ds_read_b128 v[88:91], v97 offset:36896
	ds_read_b128 v[92:95], v97 offset:41504
	v_mfma_f32_32x32x16_bf16 v[32:47], v[64:67], v[84:87], v[32:47]
	ds_read_b128 v[64:67], v96 offset:4672
	ds_read_b128 v[68:71], v97 offset:41536
	s_waitcnt lgkmcnt(3)
	v_mfma_f32_32x32x16_bf16 v[48:63], v[76:79], v[88:91], v[48:63]
	ds_read_b128 v[72:75], v96 offset:64
	ds_read_b128 v[84:87], v97 offset:36928
	s_waitcnt lgkmcnt(4)
	v_mfma_f32_32x32x16_bf16 v[16:31], v[76:79], v[92:95], v[16:31]
	ds_read_b128 v[76:79], v96 offset:96
	v_mfma_f32_32x32x16_bf16 v[32:47], v[80:83], v[88:91], v[32:47]
	ds_read_b128 v[88:91], v97 offset:36960
	v_mfma_f32_32x32x16_bf16 v[0:15], v[80:83], v[92:95], v[0:15]
	ds_read_b128 v[80:83], v96 offset:4704
	ds_read_b128 v[92:95], v97 offset:41568
	s_waitcnt lgkmcnt(0)
	s_barrier
	v_mfma_f32_32x32x16_bf16 v[48:63], v[72:75], v[84:87], v[48:63]
	v_mfma_f32_32x32x16_bf16 v[16:31], v[72:75], v[68:71], v[16:31]
	v_mfma_f32_32x32x16_bf16 v[32:47], v[64:67], v[84:87], v[32:47]
	v_mfma_f32_32x32x16_bf16 v[0:15], v[64:67], v[68:71], v[0:15]
	v_add_u32_e32 v65, s40, v102
	v_add_u32_e32 v64, 0xffffe000, v65
	v_lshrrev_b32_e32 v64, 12, v64
	v_lshrrev_b32_e32 v66, 3, v100
	v_mad_u32_u24 v64, v64, s4, s4
	v_cmp_lt_i32_e32 vcc, s5, v65
	v_and_or_b32 v66, v66, 4, v65
	v_ashrrev_i32_e32 v67, 31, v66
	v_cndmask_b32_e32 v136, 0, v64, vcc
	v_or_b32_e32 v64, s2, v101
	v_mfma_f32_32x32x16_bf16 v[48:63], v[76:79], v[88:91], v[48:63]
	v_ashrrev_i32_e32 v65, 31, v64
	v_lshl_add_u64 v[68:69], v[136:137], 2, s[0:1]
	v_lshlrev_b64 v[84:85], 1, v[64:65]
	s_movk_i32 s2, 0x1000
	s_movk_i32 s5, 0x5000
	s_mov_b32 s4, 0x8000
	v_mfma_f32_32x32x16_bf16 v[16:31], v[76:79], v[92:95], v[16:31]
	v_mfma_f32_32x32x16_bf16 v[32:47], v[80:83], v[88:91], v[32:47]
	v_mfma_f32_32x32x16_bf16 v[0:15], v[80:83], v[92:95], v[0:15]
	v_or_b32_e32 v82, 32, v66
	v_lshlrev_b64 v[66:67], 11, v[66:67]
	v_lshl_add_u64 v[66:67], s[78:79], 0, v[66:67]
	v_lshl_add_u64 v[80:81], v[64:65], 2, v[68:69]
	v_lshl_add_u64 v[64:65], v[66:67], 0, v[84:85]
	v_ashrrev_i32_e32 v83, 31, v82
	v_lshlrev_b64 v[86:87], 11, v[82:83]
	v_lshl_add_u64 v[86:87], s[78:79], 0, v[86:87]
	v_lshl_add_u64 v[86:87], v[86:87], 0, v[84:85]
	global_load_dword v104, v[80:81], off
	global_load_dword v105, v[80:81], off offset:128
	v_add_co_u32_e32 v88, vcc, 0x1000, v64
	v_addc_co_u32_e32 v89, vcc, 0, v65, vcc
	v_add_co_u32_e32 v90, vcc, 0x5000, v64
	v_addc_co_u32_e32 v91, vcc, 0, v65, vcc
	v_add_co_u32_e32 v92, vcc, 0x9000, v64
	v_addc_co_u32_e32 v93, vcc, 0, v65, vcc
	v_add_co_u32_e32 v94, vcc, 0xd000, v64
	v_addc_co_u32_e32 v95, vcc, 0, v65, vcc
	v_add_co_u32_e32 v96, vcc, 0x1000, v86
	v_addc_co_u32_e32 v97, vcc, 0, v87, vcc
	v_add_co_u32_e32 v98, vcc, 0x5000, v86
	v_addc_co_u32_e32 v99, vcc, 0, v87, vcc
	v_add_co_u32_e32 v100, vcc, 0x9000, v86
	v_addc_co_u32_e32 v101, vcc, 0, v87, vcc
	v_add_co_u32_e32 v102, vcc, 0xd000, v86
	v_addc_co_u32_e32 v103, vcc, 0, v87, vcc
	global_load_ushort v106, v[88:89], off offset:-4096
	global_load_ushort v107, v[88:89], off offset:-2048
	global_load_ushort v108, v[88:89], off
	global_load_ushort v109, v[88:89], off offset:2048
	global_load_ushort v110, v[90:91], off offset:-4096
	global_load_ushort v111, v[90:91], off offset:-2048
	global_load_ushort v112, v[90:91], off
	global_load_ushort v113, v[90:91], off offset:2048
	global_load_ushort v114, v[92:93], off offset:-4096
	global_load_ushort v115, v[92:93], off offset:-2048
	global_load_ushort v116, v[92:93], off
	global_load_ushort v117, v[92:93], off offset:2048
	global_load_ushort v118, v[94:95], off offset:-4096
	global_load_ushort v119, v[94:95], off offset:-2048
	global_load_ushort v120, v[94:95], off
	global_load_ushort v121, v[94:95], off offset:2048
	global_load_ushort v142, v[96:97], off offset:-4096
	global_load_ushort v143, v[96:97], off offset:-2048
	global_load_ushort v144, v[96:97], off
	global_load_ushort v145, v[96:97], off offset:2048
	global_load_ushort v146, v[98:99], off offset:-4096
	global_load_ushort v147, v[98:99], off offset:-2048
	global_load_ushort v148, v[98:99], off
	global_load_ushort v149, v[98:99], off offset:2048
	global_load_ushort v150, v[100:101], off offset:-4096
	global_load_ushort v151, v[100:101], off offset:-2048
	global_load_ushort v152, v[100:101], off
	global_load_ushort v153, v[100:101], off offset:2048
	global_load_ushort v154, v[102:103], off offset:-4096
	global_load_ushort v155, v[102:103], off offset:-2048
	global_load_ushort v156, v[102:103], off
	global_load_ushort v157, v[102:103], off offset:2048
	s_waitcnt vmcnt(16)
	global_load_ushort v158, v[88:89], off offset:-4032
	global_load_ushort v159, v[88:89], off offset:-1984
	global_load_ushort v160, v[88:89], off offset:64
	global_load_ushort v161, v[88:89], off offset:2112
	global_load_ushort v162, v[90:91], off offset:-4032
	global_load_ushort v163, v[90:91], off offset:-1984
	global_load_ushort v164, v[90:91], off offset:64
	global_load_ushort v165, v[90:91], off offset:2112
	global_load_ushort v166, v[92:93], off offset:-4032
	global_load_ushort v167, v[92:93], off offset:-1984
	global_load_ushort v168, v[92:93], off offset:64
	global_load_ushort v169, v[92:93], off offset:2112
	global_load_ushort v170, v[94:95], off offset:-4032
	global_load_ushort v171, v[94:95], off offset:-1984
	global_load_ushort v172, v[94:95], off offset:64
	global_load_ushort v173, v[94:95], off offset:2112
	v_lshlrev_b32_e32 v106, 16, v106
	v_fmac_f32_e32 v106, v48, v104
	v_cvt_pk_bf16_f32 v106, v106, v106
	global_store_short v[88:89], v106, off offset:-4096
	v_lshlrev_b32_e32 v107, 16, v107
	v_fmac_f32_e32 v107, v49, v104
	v_cvt_pk_bf16_f32 v107, v107, v107
	global_store_short v[88:89], v107, off offset:-2048
	v_lshlrev_b32_e32 v108, 16, v108
	v_fmac_f32_e32 v108, v50, v104
	v_cvt_pk_bf16_f32 v108, v108, v108
	global_store_short v[88:89], v108, off
	v_lshlrev_b32_e32 v109, 16, v109
	v_fmac_f32_e32 v109, v51, v104
	v_cvt_pk_bf16_f32 v109, v109, v109
	global_store_short v[88:89], v109, off offset:2048
	v_lshlrev_b32_e32 v110, 16, v110
	v_fmac_f32_e32 v110, v52, v104
	v_cvt_pk_bf16_f32 v110, v110, v110
	global_store_short v[90:91], v110, off offset:-4096
	v_lshlrev_b32_e32 v111, 16, v111
	v_fmac_f32_e32 v111, v53, v104
	v_cvt_pk_bf16_f32 v111, v111, v111
	global_store_short v[90:91], v111, off offset:-2048
	v_lshlrev_b32_e32 v112, 16, v112
	v_fmac_f32_e32 v112, v54, v104
	v_cvt_pk_bf16_f32 v112, v112, v112
	global_store_short v[90:91], v112, off
	v_lshlrev_b32_e32 v113, 16, v113
	v_fmac_f32_e32 v113, v55, v104
	v_cvt_pk_bf16_f32 v113, v113, v113
	global_store_short v[90:91], v113, off offset:2048
	v_lshlrev_b32_e32 v114, 16, v114
	v_fmac_f32_e32 v114, v56, v104
	v_cvt_pk_bf16_f32 v114, v114, v114
	global_store_short v[92:93], v114, off offset:-4096
	v_lshlrev_b32_e32 v115, 16, v115
	v_fmac_f32_e32 v115, v57, v104
	v_cvt_pk_bf16_f32 v115, v115, v115
	global_store_short v[92:93], v115, off offset:-2048
	v_lshlrev_b32_e32 v116, 16, v116
	v_fmac_f32_e32 v116, v58, v104
	v_cvt_pk_bf16_f32 v116, v116, v116
	global_store_short v[92:93], v116, off
	v_lshlrev_b32_e32 v117, 16, v117
	v_fmac_f32_e32 v117, v59, v104
	v_cvt_pk_bf16_f32 v117, v117, v117
	global_store_short v[92:93], v117, off offset:2048
	v_lshlrev_b32_e32 v118, 16, v118
	v_fmac_f32_e32 v118, v60, v104
	v_cvt_pk_bf16_f32 v118, v118, v118
	global_store_short v[94:95], v118, off offset:-4096
	v_lshlrev_b32_e32 v119, 16, v119
	v_fmac_f32_e32 v119, v61, v104
	v_cvt_pk_bf16_f32 v119, v119, v119
	global_store_short v[94:95], v119, off offset:-2048
	v_lshlrev_b32_e32 v120, 16, v120
	v_fmac_f32_e32 v120, v62, v104
	v_cvt_pk_bf16_f32 v120, v120, v120
	global_store_short v[94:95], v120, off
	v_lshlrev_b32_e32 v121, 16, v121
	v_fmac_f32_e32 v121, v63, v104
	v_cvt_pk_bf16_f32 v121, v121, v121
	global_store_short v[94:95], v121, off offset:2048
	s_waitcnt vmcnt(32)
	global_load_ushort v188, v[96:97], off offset:-4032
	global_load_ushort v189, v[96:97], off offset:-1984
	global_load_ushort v190, v[96:97], off offset:64
	global_load_ushort v191, v[96:97], off offset:2112
	global_load_ushort v192, v[98:99], off offset:-4032
	global_load_ushort v193, v[98:99], off offset:-1984
	global_load_ushort v194, v[98:99], off offset:64
	global_load_ushort v195, v[98:99], off offset:2112
	global_load_ushort v196, v[100:101], off offset:-4032
	global_load_ushort v197, v[100:101], off offset:-1984
	global_load_ushort v198, v[100:101], off offset:64
	global_load_ushort v199, v[100:101], off offset:2112
	global_load_ushort v200, v[102:103], off offset:-4032
	global_load_ushort v201, v[102:103], off offset:-1984
	global_load_ushort v202, v[102:103], off offset:64
	global_load_ushort v203, v[102:103], off offset:2112
	v_lshlrev_b32_e32 v142, 16, v142
	v_fmac_f32_e32 v142, v32, v104
	v_cvt_pk_bf16_f32 v142, v142, v142
	global_store_short v[96:97], v142, off offset:-4096
	v_lshlrev_b32_e32 v143, 16, v143
	v_fmac_f32_e32 v143, v33, v104
	v_cvt_pk_bf16_f32 v143, v143, v143
	global_store_short v[96:97], v143, off offset:-2048
	v_lshlrev_b32_e32 v144, 16, v144
	v_fmac_f32_e32 v144, v34, v104
	v_cvt_pk_bf16_f32 v144, v144, v144
	global_store_short v[96:97], v144, off
	v_lshlrev_b32_e32 v145, 16, v145
	v_fmac_f32_e32 v145, v35, v104
	v_cvt_pk_bf16_f32 v145, v145, v145
	global_store_short v[96:97], v145, off offset:2048
	v_lshlrev_b32_e32 v146, 16, v146
	v_fmac_f32_e32 v146, v36, v104
	v_cvt_pk_bf16_f32 v146, v146, v146
	global_store_short v[98:99], v146, off offset:-4096
	v_lshlrev_b32_e32 v147, 16, v147
	v_fmac_f32_e32 v147, v37, v104
	v_cvt_pk_bf16_f32 v147, v147, v147
	global_store_short v[98:99], v147, off offset:-2048
	v_lshlrev_b32_e32 v148, 16, v148
	v_fmac_f32_e32 v148, v38, v104
	v_cvt_pk_bf16_f32 v148, v148, v148
	global_store_short v[98:99], v148, off
	v_lshlrev_b32_e32 v149, 16, v149
	v_fmac_f32_e32 v149, v39, v104
	v_cvt_pk_bf16_f32 v149, v149, v149
	global_store_short v[98:99], v149, off offset:2048
	v_lshlrev_b32_e32 v150, 16, v150
	v_fmac_f32_e32 v150, v40, v104
	v_cvt_pk_bf16_f32 v150, v150, v150
	global_store_short v[100:101], v150, off offset:-4096
	v_lshlrev_b32_e32 v151, 16, v151
	v_fmac_f32_e32 v151, v41, v104
	v_cvt_pk_bf16_f32 v151, v151, v151
	global_store_short v[100:101], v151, off offset:-2048
	v_lshlrev_b32_e32 v152, 16, v152
	v_fmac_f32_e32 v152, v42, v104
	v_cvt_pk_bf16_f32 v152, v152, v152
	global_store_short v[100:101], v152, off
	v_lshlrev_b32_e32 v153, 16, v153
	v_fmac_f32_e32 v153, v43, v104
	v_cvt_pk_bf16_f32 v153, v153, v153
	global_store_short v[100:101], v153, off offset:2048
	v_lshlrev_b32_e32 v154, 16, v154
	v_fmac_f32_e32 v154, v44, v104
	v_cvt_pk_bf16_f32 v154, v154, v154
	global_store_short v[102:103], v154, off offset:-4096
	v_lshlrev_b32_e32 v155, 16, v155
	v_fmac_f32_e32 v155, v45, v104
	v_cvt_pk_bf16_f32 v155, v155, v155
	global_store_short v[102:103], v155, off offset:-2048
	v_lshlrev_b32_e32 v156, 16, v156
	v_fmac_f32_e32 v156, v46, v104
	v_cvt_pk_bf16_f32 v156, v156, v156
	global_store_short v[102:103], v156, off
	v_lshlrev_b32_e32 v157, 16, v157
	v_fmac_f32_e32 v157, v47, v104
	v_cvt_pk_bf16_f32 v157, v157, v157
	global_store_short v[102:103], v157, off offset:2048
	s_waitcnt vmcnt(48)
	v_lshlrev_b32_e32 v158, 16, v158
	v_fmac_f32_e32 v158, v16, v105
	v_cvt_pk_bf16_f32 v158, v158, v158
	global_store_short v[88:89], v158, off offset:-4032
	v_lshlrev_b32_e32 v159, 16, v159
	v_fmac_f32_e32 v159, v17, v105
	v_cvt_pk_bf16_f32 v159, v159, v159
	global_store_short v[88:89], v159, off offset:-1984
	v_lshlrev_b32_e32 v160, 16, v160
	v_fmac_f32_e32 v160, v18, v105
	v_cvt_pk_bf16_f32 v160, v160, v160
	global_store_short v[88:89], v160, off offset:64
	v_lshlrev_b32_e32 v161, 16, v161
	v_fmac_f32_e32 v161, v19, v105
	v_cvt_pk_bf16_f32 v161, v161, v161
	global_store_short v[88:89], v161, off offset:2112
	v_lshlrev_b32_e32 v162, 16, v162
	v_fmac_f32_e32 v162, v20, v105
	v_cvt_pk_bf16_f32 v162, v162, v162
	global_store_short v[90:91], v162, off offset:-4032
	v_lshlrev_b32_e32 v163, 16, v163
	v_fmac_f32_e32 v163, v21, v105
	v_cvt_pk_bf16_f32 v163, v163, v163
	global_store_short v[90:91], v163, off offset:-1984
	v_lshlrev_b32_e32 v164, 16, v164
	v_fmac_f32_e32 v164, v22, v105
	v_cvt_pk_bf16_f32 v164, v164, v164
	global_store_short v[90:91], v164, off offset:64
	v_lshlrev_b32_e32 v165, 16, v165
	v_fmac_f32_e32 v165, v23, v105
	v_cvt_pk_bf16_f32 v165, v165, v165
	global_store_short v[90:91], v165, off offset:2112
	v_lshlrev_b32_e32 v166, 16, v166
	v_fmac_f32_e32 v166, v24, v105
	v_cvt_pk_bf16_f32 v166, v166, v166
	global_store_short v[92:93], v166, off offset:-4032
	v_lshlrev_b32_e32 v167, 16, v167
	v_fmac_f32_e32 v167, v25, v105
	v_cvt_pk_bf16_f32 v167, v167, v167
	global_store_short v[92:93], v167, off offset:-1984
	v_lshlrev_b32_e32 v168, 16, v168
	v_fmac_f32_e32 v168, v26, v105
	v_cvt_pk_bf16_f32 v168, v168, v168
	global_store_short v[92:93], v168, off offset:64
	v_lshlrev_b32_e32 v169, 16, v169
	v_fmac_f32_e32 v169, v27, v105
	v_cvt_pk_bf16_f32 v169, v169, v169
	global_store_short v[92:93], v169, off offset:2112
	v_lshlrev_b32_e32 v170, 16, v170
	v_fmac_f32_e32 v170, v28, v105
	v_cvt_pk_bf16_f32 v170, v170, v170
	global_store_short v[94:95], v170, off offset:-4032
	v_lshlrev_b32_e32 v171, 16, v171
	v_fmac_f32_e32 v171, v29, v105
	v_cvt_pk_bf16_f32 v171, v171, v171
	global_store_short v[94:95], v171, off offset:-1984
	v_lshlrev_b32_e32 v172, 16, v172
	v_fmac_f32_e32 v172, v30, v105
	v_cvt_pk_bf16_f32 v172, v172, v172
	global_store_short v[94:95], v172, off offset:64
	v_lshlrev_b32_e32 v173, 16, v173
	v_fmac_f32_e32 v173, v31, v105
	v_cvt_pk_bf16_f32 v173, v173, v173
	global_store_short v[94:95], v173, off offset:2112
	s_waitcnt vmcnt(32)
	v_lshlrev_b32_e32 v188, 16, v188
	v_fmac_f32_e32 v188, v0, v105
	v_cvt_pk_bf16_f32 v188, v188, v188
	global_store_short v[96:97], v188, off offset:-4032
	v_lshlrev_b32_e32 v189, 16, v189
	v_fmac_f32_e32 v189, v1, v105
	v_cvt_pk_bf16_f32 v189, v189, v189
	global_store_short v[96:97], v189, off offset:-1984
	v_lshlrev_b32_e32 v190, 16, v190
	v_fmac_f32_e32 v190, v2, v105
	v_cvt_pk_bf16_f32 v190, v190, v190
	global_store_short v[96:97], v190, off offset:64
	v_lshlrev_b32_e32 v191, 16, v191
	v_fmac_f32_e32 v191, v3, v105
	v_cvt_pk_bf16_f32 v191, v191, v191
	global_store_short v[96:97], v191, off offset:2112
	v_lshlrev_b32_e32 v192, 16, v192
	v_fmac_f32_e32 v192, v4, v105
	v_cvt_pk_bf16_f32 v192, v192, v192
	global_store_short v[98:99], v192, off offset:-4032
	v_lshlrev_b32_e32 v193, 16, v193
	v_fmac_f32_e32 v193, v5, v105
	v_cvt_pk_bf16_f32 v193, v193, v193
	global_store_short v[98:99], v193, off offset:-1984
	v_lshlrev_b32_e32 v194, 16, v194
	v_fmac_f32_e32 v194, v6, v105
	v_cvt_pk_bf16_f32 v194, v194, v194
	global_store_short v[98:99], v194, off offset:64
	v_lshlrev_b32_e32 v195, 16, v195
	v_fmac_f32_e32 v195, v7, v105
	v_cvt_pk_bf16_f32 v195, v195, v195
	global_store_short v[98:99], v195, off offset:2112
	v_lshlrev_b32_e32 v196, 16, v196
	v_fmac_f32_e32 v196, v8, v105
	v_cvt_pk_bf16_f32 v196, v196, v196
	global_store_short v[100:101], v196, off offset:-4032
	v_lshlrev_b32_e32 v197, 16, v197
	v_fmac_f32_e32 v197, v9, v105
	v_cvt_pk_bf16_f32 v197, v197, v197
	global_store_short v[100:101], v197, off offset:-1984
	v_lshlrev_b32_e32 v198, 16, v198
	v_fmac_f32_e32 v198, v10, v105
	v_cvt_pk_bf16_f32 v198, v198, v198
	global_store_short v[100:101], v198, off offset:64
	v_lshlrev_b32_e32 v199, 16, v199
	v_fmac_f32_e32 v199, v11, v105
	v_cvt_pk_bf16_f32 v199, v199, v199
	global_store_short v[100:101], v199, off offset:2112
	v_lshlrev_b32_e32 v200, 16, v200
	v_fmac_f32_e32 v200, v12, v105
	v_cvt_pk_bf16_f32 v200, v200, v200
	global_store_short v[102:103], v200, off offset:-4032
	v_lshlrev_b32_e32 v201, 16, v201
	v_fmac_f32_e32 v201, v13, v105
	v_cvt_pk_bf16_f32 v201, v201, v201
	global_store_short v[102:103], v201, off offset:-1984
	v_lshlrev_b32_e32 v202, 16, v202
	v_fmac_f32_e32 v202, v14, v105
	v_cvt_pk_bf16_f32 v202, v202, v202
	global_store_short v[102:103], v202, off offset:64
	v_lshlrev_b32_e32 v203, 16, v203
	v_fmac_f32_e32 v203, v15, v105
	v_cvt_pk_bf16_f32 v203, v203, v203
	global_store_short v[102:103], v203, off offset:2112
	v_readlane_b32 s2, v252, 33
	s_add_i32 s44, s44, s2
	s_cmp_gt_i32 s44, 31
	s_cbranch_scc0 .LBB0_344

.LBB0_381:
	s_barrier
	s_mulk_i32 s3, 0x2400
	v_add3_u32 v190, v143, s3, v142
	v_add_u32_e32 v191, 0x6800, v190
	v_add_u32_e32 v192, 0x7a00, v190
	ds_read2_b64 v[194:197], v191 offset1:2
	ds_read2_b64 v[198:201], v192 offset1:2
	ds_read2_b64 v[202:205], v191 offset0:4 offset1:6
	ds_read2_b64 v[206:209], v192 offset0:4 offset1:6
	ds_read2_b64 v[210:213], v191 offset0:8 offset1:10
	ds_read2_b64 v[214:217], v192 offset0:8 offset1:10
	ds_read2_b64 v[218:221], v191 offset0:12 offset1:14
	ds_read2_b64 v[222:225], v192 offset0:12 offset1:14
	v_sub_f32_e32 v32, v32, v151
	v_sub_f32_e32 v33, v33, v151
	v_sub_f32_e32 v34, v34, v151
	v_sub_f32_e32 v35, v35, v151
	v_sub_f32_e32 v36, v36, v151
	v_sub_f32_e32 v37, v37, v151
	v_sub_f32_e32 v38, v38, v151
	v_sub_f32_e32 v39, v39, v151
	v_exp_f32_e32 v32, v32
	v_exp_f32_e32 v33, v33
	v_exp_f32_e32 v34, v34
	v_exp_f32_e32 v35, v35
	v_exp_f32_e32 v36, v36
	v_exp_f32_e32 v37, v37
	v_exp_f32_e32 v38, v38
	v_exp_f32_e32 v39, v39
	v_cvt_pk_bf16_f32 v160, v32, v33
	v_cvt_pk_bf16_f32 v161, v34, v35
	v_cvt_pk_bf16_f32 v162, v36, v37
	v_cvt_pk_bf16_f32 v163, v38, v39
	v_add_f32_e32 v168, v32, v33
	v_add_f32_e32 v169, v34, v35
	v_add_f32_e32 v168, v168, v36
	v_add_f32_e32 v169, v169, v37
	v_add_f32_e32 v168, v168, v38
	v_add_f32_e32 v169, v169, v39
	s_waitcnt lgkmcnt(6)
	v_mfma_f32_32x32x16_bf16 v[16:31], v[194:197], v[160:163], v[16:31]
	v_mfma_f32_32x32x16_bf16 v[0:15], v[198:201], v[160:163], v[0:15]
	v_sub_f32_e32 v40, v40, v151
	v_sub_f32_e32 v41, v41, v151
	v_sub_f32_e32 v42, v42, v151
	v_sub_f32_e32 v43, v43, v151
	v_sub_f32_e32 v44, v44, v151
	v_sub_f32_e32 v45, v45, v151
	v_sub_f32_e32 v46, v46, v151
	v_sub_f32_e32 v47, v47, v151
	v_exp_f32_e32 v40, v40
	v_exp_f32_e32 v41, v41
	v_exp_f32_e32 v42, v42
	v_exp_f32_e32 v43, v43
	v_exp_f32_e32 v44, v44
	v_exp_f32_e32 v45, v45
	v_exp_f32_e32 v46, v46
	v_exp_f32_e32 v47, v47
	v_cvt_pk_bf16_f32 v164, v40, v41
	v_cvt_pk_bf16_f32 v165, v42, v43
	v_cvt_pk_bf16_f32 v166, v44, v45
	v_cvt_pk_bf16_f32 v167, v46, v47
	v_add_f32_e32 v168, v168, v40
	v_add_f32_e32 v169, v169, v41
	v_add_f32_e32 v168, v168, v42
	v_add_f32_e32 v169, v169, v43
	v_add_f32_e32 v168, v168, v44
	v_add_f32_e32 v169, v169, v45
	v_add_f32_e32 v168, v168, v46
	v_add_f32_e32 v169, v169, v47
	s_waitcnt lgkmcnt(4)
	v_mfma_f32_32x32x16_bf16 v[16:31], v[202:205], v[164:167], v[16:31]
	v_mfma_f32_32x32x16_bf16 v[0:15], v[206:209], v[164:167], v[0:15]
	v_sub_f32_e32 v48, v48, v151
	v_sub_f32_e32 v49, v49, v151
	v_sub_f32_e32 v50, v50, v151
	v_sub_f32_e32 v51, v51, v151
	v_sub_f32_e32 v52, v52, v151
	v_sub_f32_e32 v53, v53, v151
	v_sub_f32_e32 v54, v54, v151
	v_sub_f32_e32 v55, v55, v151
	v_exp_f32_e32 v48, v48
	v_exp_f32_e32 v49, v49
	v_exp_f32_e32 v50, v50
	v_exp_f32_e32 v51, v51
	v_exp_f32_e32 v52, v52
	v_exp_f32_e32 v53, v53
	v_exp_f32_e32 v54, v54
	v_exp_f32_e32 v55, v55
	v_cvt_pk_bf16_f32 v160, v48, v49
	v_cvt_pk_bf16_f32 v161, v50, v51
	v_cvt_pk_bf16_f32 v162, v52, v53
	v_cvt_pk_bf16_f32 v163, v54, v55
	v_add_f32_e32 v168, v168, v48
	v_add_f32_e32 v169, v169, v49
	v_add_f32_e32 v168, v168, v50
	v_add_f32_e32 v169, v169, v51
	v_add_f32_e32 v168, v168, v52
	v_add_f32_e32 v169, v169, v53
	v_add_f32_e32 v168, v168, v54
	v_add_f32_e32 v169, v169, v55
	s_waitcnt lgkmcnt(2)
	v_mfma_f32_32x32x16_bf16 v[16:31], v[210:213], v[160:163], v[16:31]
	v_mfma_f32_32x32x16_bf16 v[0:15], v[214:217], v[160:163], v[0:15]
	v_sub_f32_e32 v56, v56, v151
	v_sub_f32_e32 v57, v57, v151
	v_sub_f32_e32 v58, v58, v151
	v_sub_f32_e32 v59, v59, v151
	v_sub_f32_e32 v60, v60, v151
	v_sub_f32_e32 v61, v61, v151
	v_sub_f32_e32 v62, v62, v151
	v_sub_f32_e32 v63, v63, v151
	v_exp_f32_e32 v56, v56
	v_exp_f32_e32 v57, v57
	v_exp_f32_e32 v58, v58
	v_exp_f32_e32 v59, v59
	v_exp_f32_e32 v60, v60
	v_exp_f32_e32 v61, v61
	v_exp_f32_e32 v62, v62
	v_exp_f32_e32 v63, v63
	v_cvt_pk_bf16_f32 v164, v56, v57
	v_cvt_pk_bf16_f32 v165, v58, v59
	v_cvt_pk_bf16_f32 v166, v60, v61
	v_cvt_pk_bf16_f32 v167, v62, v63
	v_add_f32_e32 v168, v168, v56
	v_add_f32_e32 v169, v169, v57
	v_add_f32_e32 v168, v168, v58
	v_add_f32_e32 v169, v169, v59
	v_add_f32_e32 v168, v168, v60
	v_add_f32_e32 v169, v169, v61
	v_add_f32_e32 v168, v168, v62
	v_add_f32_e32 v169, v169, v63
	v_add_f32_e32 v168, v168, v169
	v_add_f32_e32 v119, v119, v168
	s_add_i32 s1, s1, 64
	s_cmpk_lg_i32 s1, 0x11c0
	s_waitcnt lgkmcnt(0)
	s_barrier
	v_mfma_f32_32x32x16_bf16 v[16:31], v[218:221], v[164:167], v[16:31]
	v_mfma_f32_32x32x16_bf16 v[0:15], v[222:225], v[164:167], v[0:15]
	s_cbranch_scc0 .LBB0_383
	s_mov_b32 s3, s2
	s_branch .LBB0_377
